# P3 conv/attention order mixing keyed on workgroup id bit 3 (within each XCD) instead of bit 0 (XCD parity)
# speedup vs baseline: 1.0007x; 1.0007x over previous
; #define LAS __attribute__((address_space(3)))
; __global__ void __launch_bounds__(512, 2) hybrid_fwd(Args args) {
;     ...
;     DUP_BEGIN(3) if (IN(3)) {
;         if (sub & 1) for (int cu = F.bid; cu < 1024; cu += F.G) {
;             if (cu < 512) conv_unit<16384, 1>(F, cu, FRS, F0 + 1024, args.in[15], UT, UT, TOKP, dry);
;             else conv_unit<4096, 4>(F, cu - 512, FRP, F0, args.in[15], UT, UT, 0, dry);
;         }
;         __syncthreads();
;         int cur_head = -1; LAS float* tab = (LAS float*)(F.lds + F.wave * 2560); LAS unsigned char* wl = F.lds + 20480 + F.wave * ATT_WAVE_LDS;
;         if (sub & 2) {
;             if ((F.G & 7) == 0) {
;                 const int h = F.bid & 7, NWV = (F.G >> 3) * 8;
;                 for (int e = (F.bid >> 3) * 8 + F.wave; e < 1024; e += NWV)
;                     attn_unit(e >> 1, h, e & 1, Qb, Kb, VT, Qb, args.in[4], tab, wl, F.lane, cur_head, dry);
;             } else {
;                 for (int u = gw; u < 8192; u += NGW) attn_unit(u >> 4, (u >> 1) & 7, u & 1, Qb, Kb, VT, Qb, args.in[4], tab, wl, F.lane, cur_head, dry);
;             }
;         }
;     }
.LBB0_753:
	v_mov_b32_e32 v255, 0
	v_mov_b32_e32 v247, 1
	s_cmp_lt_i32 s84, 4
	s_cselect_b64 s[2:3], -1, 0
	s_and_b64 s[0:1], s[2:3], s[0:1]
	v_writelane_b32 v246, s0, 34
	s_andn2_b64 vcc, exec, s[0:1]
	s_nop 0
	v_writelane_b32 v246, s1, 35
	s_cbranch_vccnz .LBB0_1110
	v_writelane_b32 v246, s96, 30
	s_cmpk_gt_i32 s33, 0x3ff
	s_nop 0
	v_writelane_b32 v246, s97, 31
	v_writelane_b32 v246, s87, 36
	v_writelane_b32 v246, s94, 37
	s_nop 1
	v_writelane_b32 v246, s95, 38
	v_writelane_b32 v246, s84, 39
	s_nop 1
	v_writelane_b32 v246, s85, 40
	s_cbranch_scc1 .LBB0_1054
	v_mov_b32_e32 v247, 0
	s_bitcmp1_b32 s33, 3
	s_cbranch_scc1 .LBB0_1054

; #define LAS __attribute__((address_space(3)))
; __global__ void __launch_bounds__(512, 2) hybrid_fwd(Args args) {
;     ...
;     DUP_BEGIN(3) if (IN(3)) {
;         if (sub & 1) for (int cu = F.bid; cu < 1024; cu += F.G) {
;             if (cu < 512) conv_unit<16384, 1>(F, cu, FRS, F0 + 1024, args.in[15], UT, UT, TOKP, dry);
;             else conv_unit<4096, 4>(F, cu - 512, FRP, F0, args.in[15], UT, UT, 0, dry);
;         }
;         __syncthreads();
;         int cur_head = -1; LAS float* tab = (LAS float*)(F.lds + F.wave * 2560); LAS unsigned char* wl = F.lds + 20480 + F.wave * ATT_WAVE_LDS;
;         if (sub & 2) {
;             if ((F.G & 7) == 0) {
;                 const int h = F.bid & 7, NWV = (F.G >> 3) * 8;
;                 for (int e = (F.bid >> 3) * 8 + F.wave; e < 1024; e += NWV)
;                     attn_unit(e >> 1, h, e & 1, Qb, Kb, VT, Qb, args.in[4], tab, wl, F.lane, cur_head, dry);
;             } else {
;                 for (int u = gw; u < 8192; u += NGW) attn_unit(u >> 4, (u >> 1) & 7, u & 1, Qb, Kb, VT, Qb, args.in[4], tab, wl, F.lane, cur_head, dry);
;             }
;         }
;     }
.LBB0_1110:
	v_cmp_ne_u32_e32 vcc, 0, v247
	s_cbranch_vccnz .Lp3_done
	s_bitcmp1_b32 s33, 3
	s_cbranch_scc0 .Lp3_done
	v_mov_b32_e32 v247, 1
	s_sub_u32 s0, s96, 0xd8
	s_subb_u32 s1, s97, 0
	s_load_dwordx2 s[30:31], s[0:1], 0x78
	s_add_u32 s34, s82, 0x60000
	s_addc_u32 s35, s83, 0
	s_add_u32 s40, s82, 0xc800000
	s_addc_u32 s41, s83, 0
	s_waitcnt vmcnt(0) lgkmcnt(0)
	s_barrier
	s_branch .Lp3_conv_start
